# FFN up-projection epilogues: output lanes permuted (ds_bpermute of data+address) so 4 consecutive lanes store one row's contiguous 64 B; stores deferred by one to hide the permute latency
# baseline (speedup 1.0000x reference)
; DI float sigmoidf_(float v) { return __builtin_amdgcn_rcpf(1.f + __builtin_amdgcn_exp2f(-v * 1.4426950408889634f)); }
; DI u32x4 pack8(f32x4 a, f32x4 b) { u32x4 w; w.x = cvtpk(a[0], a[1]); w.y = cvtpk(a[2], a[3]); w.z = cvtpk(b[0], b[1]); w.w = cvtpk(b[2], b[3]); return w; }
;   DI void operator()(const f32x4 (&acc)[2][2][4][2], const Unit& u, int wr, int wc, int fr, int fq) const {
;     const int row0 = u.pm * 256 + wr * 64 + fr; const int hcol = u.pn * 128 + wc * 32 + 8 * fq;
;     float rs[8];
; #pragma unroll
;     for (int i = 0; i < 8; ++i) rs[i] = ssq[row0 + (i >> 2) * 128 + (i & 3) * 16];
; #pragma unroll
;     for (int ai = 0; ai < 2; ++ai)
; #pragma unroll
;       for (int m = 0; m < 4; ++m) {
;         const int row = row0 + ai * 128 + m * 16;
;         const float rstd = rsqrtf(rs[ai * 4 + m] * (1.f / DM) + EPSN);
;         f32x4 o[2];
; #pragma unroll
;         for (int n = 0; n < 2; ++n) {
;           const f32x4 a = acc[ai][0][m][n] * rstd, b = acc[ai][1][m][n] * rstd;
; #pragma unroll
;           for (int e = 0; e < 4; ++e) o[n][e] = a[e] * sigmoidf_(a[e]) * b[e];
;         }
;         __builtin_nontemporal_store(pack8(o[0], o[1]), (u32x4*)(H + (size_t)row * DFF + hcol));
;       }
.LBB0_455:
	v_and_b32_e32 v216, 63, v200
	v_lshrrev_b32_e32 v217, 2, v216
	v_and_b32_e32 v216, 3, v216
	v_lshl_add_u32 v216, v216, 4, v217
	v_lshlrev_b32_e32 v216, 2, v216
	v_lshl_add_u32 v144, s8, 8, v150
	v_ashrrev_i32_e32 v145, 31, v144
	v_lshl_add_u64 v[148:149], v[144:145], 2, s[56:57]
	global_load_dword v162, v[148:149], off
	global_load_dword v163, v[148:149], off offset:64
	global_load_dword v175, v[148:149], off offset:128
	global_load_dword v176, v[148:149], off offset:192
	global_load_dword v177, v[148:149], off offset:512
	global_load_dword v178, v[148:149], off offset:576
	global_load_dword v157, v[148:149], off offset:640
	global_load_dword v145, v[148:149], off offset:704
	v_lshl_or_b32 v158, s9, 7, v152
	v_readlane_b32 s8, v252, 3
	v_readlane_b32 s9, v252, 4
	v_ashrrev_i32_e32 v159, 31, v158
	v_add_u32_e32 v174, 0x80, v144
	v_mov_b64_e32 v[146:147], s[8:9]
	v_mad_i64_i32 v[160:161], s[8:9], v144, s40, v[146:147]
	s_waitcnt vmcnt(0)
	v_fmamk_f32 v148, v162, 0x3a800000, v156
	v_fmamk_f32 v149, v163, 0x3a800000, v156
	v_mul_f32_e32 v162, 0x4b800000, v148
	v_cmp_gt_f32_e32 vcc, s39, v148
	v_mul_f32_e32 v163, 0x4b800000, v149
	v_cmp_gt_f32_e64 s[8:9], s39, v149
	v_cndmask_b32_e32 v148, v148, v162, vcc
	v_rsq_f32_e32 v162, v148
	v_cndmask_b32_e64 v149, v149, v163, s[8:9]
	v_rsq_f32_e32 v163, v149
	v_lshlrev_b64 v[148:149], 1, v[158:159]
	v_lshl_add_u64 v[158:159], v[160:161], 0, v[148:149]
	v_mul_f32_e32 v160, 0x45800000, v162
	v_mul_f32_e32 v161, 0x45800000, v163
	v_cndmask_b32_e32 v160, v162, v160, vcc
	v_cndmask_b32_e64 v162, v163, v161, s[8:9]
	v_pk_mul_f32 v[124:125], v[124:125], v[160:161] op_sel_hi:[1,0]
	v_pk_mul_f32 v[126:127], v[126:127], v[160:161] op_sel_hi:[1,0]
	v_pk_mul_f32 v[120:121], v[120:121], v[160:161] op_sel_hi:[1,0]
	v_pk_mul_f32 v[122:123], v[122:123], v[160:161] op_sel_hi:[1,0]
	v_pk_mul_f32 v[112:113], v[112:113], v[160:161] op_sel_hi:[1,0]
	v_pk_mul_f32 v[114:115], v[114:115], v[160:161] op_sel_hi:[1,0]
	v_pk_mul_f32 v[108:109], v[108:109], v[160:161] op_sel_hi:[1,0]
	v_pk_mul_f32 v[110:111], v[110:111], v[160:161] op_sel_hi:[1,0]
	v_pk_mul_f32 v[116:117], v[116:117], v[162:163] op_sel_hi:[1,0]
	v_pk_mul_f32 v[100:101], v[100:101], v[162:163] op_sel_hi:[1,0]
	v_pk_mul_f32 v[118:119], v[118:119], v[162:163] op_sel_hi:[1,0]
	v_mul_f32_e32 v160, 0xbfb8aa3b, v124
	v_mul_f32_e32 v161, 0xbfb8aa3b, v125
	v_mul_f32_e32 v163, 0xbfb8aa3b, v126
	v_mul_f32_e32 v164, 0xbfb8aa3b, v127
	v_mul_f32_e32 v165, 0xbfb8aa3b, v120
	v_mul_f32_e32 v166, 0xbfb8aa3b, v121
	v_mul_f32_e32 v167, 0xbfb8aa3b, v122
	v_mul_f32_e32 v168, 0xbfb8aa3b, v123
	v_mul_f32_e32 v169, 0xbfb8aa3b, v116
	v_exp_f32_e32 v160, v160
	v_exp_f32_e32 v161, v161
	v_exp_f32_e32 v163, v163
	v_exp_f32_e32 v164, v164
	v_exp_f32_e32 v165, v165
	v_exp_f32_e32 v166, v166
	v_exp_f32_e32 v167, v167
	v_exp_f32_e32 v168, v168
	v_exp_f32_e32 v169, v169
	v_add_f32_e32 v160, 1.0, v160
	v_add_f32_e32 v161, 1.0, v161
	v_add_f32_e32 v163, 1.0, v163
	v_add_f32_e32 v173, 1.0, v164
	v_add_f32_e32 v179, 1.0, v165
	v_add_f32_e32 v180, 1.0, v166
	v_add_f32_e32 v181, 1.0, v167
	v_add_f32_e32 v182, 1.0, v168
	v_add_f32_e32 v183, 1.0, v169
	v_rcp_f32_e32 v160, v160
	v_rcp_f32_e32 v161, v161
	v_rcp_f32_e32 v164, v163
	v_rcp_f32_e32 v165, v173
	v_rcp_f32_e32 v166, v179
	v_rcp_f32_e32 v167, v180
	v_rcp_f32_e32 v168, v181
	v_rcp_f32_e32 v169, v182
	v_mul_f32_e32 v171, 0xbfb8aa3b, v118
	v_mul_f32_e32 v172, 0xbfb8aa3b, v119
	v_exp_f32_e32 v171, v171
	v_exp_f32_e32 v172, v172
	v_pk_mul_f32 v[124:125], v[124:125], v[160:161]
	v_pk_mul_f32 v[126:127], v[126:127], v[164:165]
	v_pk_mul_f32 v[120:121], v[120:121], v[166:167]
	v_pk_mul_f32 v[122:123], v[122:123], v[168:169]
	v_pk_mul_f32 v[112:113], v[112:113], v[124:125]
	v_pk_mul_f32 v[114:115], v[114:115], v[126:127]
	v_pk_mul_f32 v[120:121], v[108:109], v[120:121]
	v_pk_mul_f32 v[122:123], v[110:111], v[122:123]
	v_add_f32_e32 v185, 1.0, v171
	v_add_f32_e32 v186, 1.0, v172
	v_cvt_pk_bf16_f32 v108, v112, v113
	v_cvt_pk_bf16_f32 v109, v114, v115
	v_cvt_pk_bf16_f32 v110, v120, v121
	v_cvt_pk_bf16_f32 v111, v122, v123
	v_pk_mul_f32 v[104:105], v[104:105], v[162:163] op_sel_hi:[1,0]
	v_rcp_f32_e32 v172, v185
	v_rcp_f32_e32 v173, v186
	ds_bpermute_b32 v204, v216, v158
	ds_bpermute_b32 v205, v216, v159
	ds_bpermute_b32 v208, v216, v108
	ds_bpermute_b32 v209, v216, v109
	ds_bpermute_b32 v210, v216, v110
	ds_bpermute_b32 v211, v216, v111
	v_mul_f32_e32 v170, 0xbfb8aa3b, v117
	v_pk_mul_f32 v[102:103], v[102:103], v[162:163] op_sel_hi:[1,0]
	v_mul_f32_e32 v110, 0xbfb8aa3b, v104
	v_mul_f32_e32 v111, 0xbfb8aa3b, v105
	v_exp_f32_e32 v110, v110
	v_exp_f32_e32 v111, v111
	v_pk_mul_f32 v[108:109], v[118:119], v[172:173]
	v_pk_mul_f32 v[106:107], v[106:107], v[162:163] op_sel_hi:[1,0]
	v_exp_f32_e32 v170, v170
	v_pk_mul_f32 v[102:103], v[102:103], v[108:109]
	v_add_f32_e32 v108, 1.0, v110
	v_add_f32_e32 v109, 1.0, v111
	v_mul_f32_e32 v110, 0xbfb8aa3b, v106
	v_mul_f32_e32 v111, 0xbfb8aa3b, v107
	v_exp_f32_e32 v110, v110
	v_exp_f32_e32 v111, v111
	v_add_f32_e32 v184, 1.0, v170
	v_rcp_f32_e32 v170, v183
	v_rcp_f32_e32 v171, v184
	v_rcp_f32_e32 v108, v108
	v_rcp_f32_e32 v109, v109
	v_add_f32_e32 v110, 1.0, v110
	v_add_f32_e32 v111, 1.0, v111
	v_rcp_f32_e32 v110, v110
	v_rcp_f32_e32 v111, v111
	v_pk_mul_f32 v[116:117], v[116:117], v[170:171]
	v_pk_mul_f32 v[104:105], v[104:105], v[108:109]
	v_pk_mul_f32 v[96:97], v[96:97], v[162:163] op_sel_hi:[1,0]
	v_pk_mul_f32 v[100:101], v[100:101], v[116:117]
	v_pk_mul_f32 v[104:105], v[96:97], v[104:105]
	v_pk_mul_f32 v[96:97], v[106:107], v[110:111]
	v_pk_mul_f32 v[98:99], v[98:99], v[162:163] op_sel_hi:[1,0]
	v_or_b32_e32 v108, 16, v144
	v_pk_mul_f32 v[106:107], v[98:99], v[96:97]
	v_cvt_pk_bf16_f32 v96, v100, v101
	v_fmamk_f32 v100, v175, 0x3a800000, v156
	v_mul_f32_e32 v101, 0x4b800000, v100
	v_cmp_gt_f32_e32 vcc, s39, v100
	v_cvt_pk_bf16_f32 v97, v102, v103
	v_cvt_pk_bf16_f32 v98, v104, v105
	v_cndmask_b32_e32 v100, v100, v101, vcc
	v_rsq_f32_e32 v102, v100
	v_mad_i64_i32 v[100:101], s[8:9], v108, s40, v[146:147]
	v_cvt_pk_bf16_f32 v99, v106, v107
	v_mul_f32_e32 v103, 0x45800000, v102
	v_cndmask_b32_e32 v102, v102, v103, vcc
	v_pk_mul_f32 v[92:93], v[92:93], v[102:103] op_sel_hi:[1,0]
	v_lshl_add_u64 v[100:101], v[100:101], 0, v[148:149]
	v_mul_f32_e32 v103, 0xbfb8aa3b, v92
	v_exp_f32_e32 v103, v103
	v_mul_f32_e32 v104, 0xbfb8aa3b, v93
	v_exp_f32_e32 v104, v104
	ds_bpermute_b32 v206, v216, v100
	ds_bpermute_b32 v207, v216, v101
	ds_bpermute_b32 v212, v216, v96
	ds_bpermute_b32 v213, v216, v97
	ds_bpermute_b32 v214, v216, v98
	ds_bpermute_b32 v215, v216, v99
	s_waitcnt lgkmcnt(6)
; DI float sigmoidf_(float v) { return __builtin_amdgcn_rcpf(1.f + __builtin_amdgcn_exp2f(-v * 1.4426950408889634f)); }
; DI u32x4 pack8(f32x4 a, f32x4 b) { u32x4 w; w.x = cvtpk(a[0], a[1]); w.y = cvtpk(a[2], a[3]); w.z = cvtpk(b[0], b[1]); w.w = cvtpk(b[2], b[3]); return w; }
;   DI void operator()(const f32x4 (&acc)[2][2][4][2], const Unit& u, int wr, int wc, int fr, int fq) const {
;     const int row0 = u.pm * 256 + wr * 64 + fr; const int hcol = u.pn * 128 + wc * 32 + 8 * fq;
;     float rs[8];
; #pragma unroll
;     for (int i = 0; i < 8; ++i) rs[i] = ssq[row0 + (i >> 2) * 128 + (i & 3) * 16];
; #pragma unroll
;     for (int ai = 0; ai < 2; ++ai)
; #pragma unroll
;       for (int m = 0; m < 4; ++m) {
;         const int row = row0 + ai * 128 + m * 16;
;         const float rstd = rsqrtf(rs[ai * 4 + m] * (1.f / DM) + EPSN);
;         f32x4 o[2];
; #pragma unroll
;         for (int n = 0; n < 2; ++n) {
;           const f32x4 a = acc[ai][0][m][n] * rstd, b = acc[ai][1][m][n] * rstd;
; #pragma unroll
;           for (int e = 0; e < 4; ++e) o[n][e] = a[e] * sigmoidf_(a[e]) * b[e];
;         }
;         __builtin_nontemporal_store(pack8(o[0], o[1]), (u32x4*)(H + (size_t)row * DFF + hcol));
;       }
	global_store_dwordx4 v[204:205], v[208:211], off nt
	v_pk_mul_f32 v[94:95], v[94:95], v[102:103] op_sel_hi:[1,0]
	v_pk_mul_f32 v[84:85], v[84:85], v[102:103] op_sel_hi:[1,0]
	v_mul_f32_e32 v98, 0xbfb8aa3b, v94
	v_mul_f32_e32 v99, 0xbfb8aa3b, v95
	v_exp_f32_e32 v98, v98
	v_exp_f32_e32 v99, v99
	v_add_f32_e32 v96, 1.0, v103
	v_add_f32_e32 v97, 1.0, v104
	v_rcp_f32_e32 v96, v96
	v_rcp_f32_e32 v97, v97
	v_add_f32_e32 v98, 1.0, v98
	v_add_f32_e32 v99, 1.0, v99
	v_rcp_f32_e32 v98, v98
	v_rcp_f32_e32 v99, v99
	v_pk_mul_f32 v[92:93], v[92:93], v[96:97]
	v_pk_mul_f32 v[88:89], v[88:89], v[102:103] op_sel_hi:[1,0]
	v_pk_mul_f32 v[84:85], v[84:85], v[92:93]
	v_pk_mul_f32 v[92:93], v[94:95], v[98:99]
	v_mul_f32_e32 v94, 0xbfb8aa3b, v88
	v_mul_f32_e32 v95, 0xbfb8aa3b, v89
	v_exp_f32_e32 v94, v94
	v_exp_f32_e32 v95, v95
	v_pk_mul_f32 v[86:87], v[86:87], v[102:103] op_sel_hi:[1,0]
	v_pk_mul_f32 v[90:91], v[90:91], v[102:103] op_sel_hi:[1,0]
	v_pk_mul_f32 v[86:87], v[86:87], v[92:93]
	v_add_f32_e32 v92, 1.0, v94
	v_add_f32_e32 v93, 1.0, v95
	v_mul_f32_e32 v94, 0xbfb8aa3b, v90
	v_mul_f32_e32 v95, 0xbfb8aa3b, v91
	v_exp_f32_e32 v94, v94
	v_exp_f32_e32 v95, v95
	v_rcp_f32_e32 v92, v92
	v_rcp_f32_e32 v93, v93
	v_add_f32_e32 v94, 1.0, v94
	v_add_f32_e32 v95, 1.0, v95
	v_rcp_f32_e32 v94, v94
	v_rcp_f32_e32 v95, v95
	v_pk_mul_f32 v[88:89], v[88:89], v[92:93]
	v_pk_mul_f32 v[80:81], v[80:81], v[102:103] op_sel_hi:[1,0]
	v_pk_mul_f32 v[82:83], v[82:83], v[102:103] op_sel_hi:[1,0]
	v_pk_mul_f32 v[88:89], v[80:81], v[88:89]
	v_pk_mul_f32 v[80:81], v[90:91], v[94:95]
	v_or_b32_e32 v92, 32, v144
	v_pk_mul_f32 v[90:91], v[82:83], v[80:81]
	v_cvt_pk_bf16_f32 v80, v84, v85
	v_fmamk_f32 v84, v176, 0x3a800000, v156
	v_mul_f32_e32 v85, 0x4b800000, v84
	v_cmp_gt_f32_e32 vcc, s39, v84
	v_cvt_pk_bf16_f32 v81, v86, v87
	v_cvt_pk_bf16_f32 v82, v88, v89
	v_cndmask_b32_e32 v84, v84, v85, vcc
	v_rsq_f32_e32 v86, v84
	v_mad_i64_i32 v[84:85], s[8:9], v92, s40, v[146:147]
	v_cvt_pk_bf16_f32 v83, v90, v91
	v_mul_f32_e32 v87, 0x45800000, v86
	v_cndmask_b32_e32 v86, v86, v87, vcc
	v_pk_mul_f32 v[76:77], v[76:77], v[86:87] op_sel_hi:[1,0]
	v_lshl_add_u64 v[84:85], v[84:85], 0, v[148:149]
	v_mul_f32_e32 v87, 0xbfb8aa3b, v76
	v_exp_f32_e32 v87, v87
	v_mul_f32_e32 v88, 0xbfb8aa3b, v77
	v_exp_f32_e32 v88, v88
	ds_bpermute_b32 v204, v216, v84
	ds_bpermute_b32 v205, v216, v85
	ds_bpermute_b32 v208, v216, v80
	ds_bpermute_b32 v209, v216, v81
	ds_bpermute_b32 v210, v216, v82
	ds_bpermute_b32 v211, v216, v83
	s_waitcnt lgkmcnt(6)
	global_store_dwordx4 v[206:207], v[212:215], off nt
	v_pk_mul_f32 v[78:79], v[78:79], v[86:87] op_sel_hi:[1,0]
	v_pk_mul_f32 v[68:69], v[68:69], v[86:87] op_sel_hi:[1,0]
	v_mul_f32_e32 v82, 0xbfb8aa3b, v78
	v_mul_f32_e32 v83, 0xbfb8aa3b, v79
	v_exp_f32_e32 v82, v82
	v_exp_f32_e32 v83, v83
	v_add_f32_e32 v80, 1.0, v87
	v_add_f32_e32 v81, 1.0, v88
	v_rcp_f32_e32 v80, v80
	v_rcp_f32_e32 v81, v81
	v_add_f32_e32 v82, 1.0, v82
	v_add_f32_e32 v83, 1.0, v83
	v_rcp_f32_e32 v82, v82
	v_rcp_f32_e32 v83, v83
	v_pk_mul_f32 v[76:77], v[76:77], v[80:81]
	v_pk_mul_f32 v[72:73], v[72:73], v[86:87] op_sel_hi:[1,0]
	v_pk_mul_f32 v[68:69], v[68:69], v[76:77]
	v_pk_mul_f32 v[76:77], v[78:79], v[82:83]
	v_mul_f32_e32 v78, 0xbfb8aa3b, v72
	v_mul_f32_e32 v79, 0xbfb8aa3b, v73
	v_exp_f32_e32 v78, v78
	v_exp_f32_e32 v79, v79
	v_pk_mul_f32 v[70:71], v[70:71], v[86:87] op_sel_hi:[1,0]
	v_pk_mul_f32 v[74:75], v[74:75], v[86:87] op_sel_hi:[1,0]
	v_pk_mul_f32 v[70:71], v[70:71], v[76:77]
	v_add_f32_e32 v76, 1.0, v78
	v_add_f32_e32 v77, 1.0, v79
	v_mul_f32_e32 v78, 0xbfb8aa3b, v74
	v_mul_f32_e32 v79, 0xbfb8aa3b, v75
	v_exp_f32_e32 v78, v78
	v_exp_f32_e32 v79, v79
	v_rcp_f32_e32 v76, v76
	v_rcp_f32_e32 v77, v77
	v_add_f32_e32 v78, 1.0, v78
	v_add_f32_e32 v79, 1.0, v79
	v_rcp_f32_e32 v78, v78
	v_rcp_f32_e32 v79, v79
	v_pk_mul_f32 v[72:73], v[72:73], v[76:77]
	v_pk_mul_f32 v[64:65], v[64:65], v[86:87] op_sel_hi:[1,0]
	v_pk_mul_f32 v[66:67], v[66:67], v[86:87] op_sel_hi:[1,0]
	v_pk_mul_f32 v[72:73], v[64:65], v[72:73]
	v_pk_mul_f32 v[64:65], v[74:75], v[78:79]
	v_or_b32_e32 v76, 48, v144
	v_pk_mul_f32 v[74:75], v[66:67], v[64:65]
	v_cvt_pk_bf16_f32 v64, v68, v69
	v_fmamk_f32 v68, v177, 0x3a800000, v156
	v_mul_f32_e32 v69, 0x4b800000, v68
	v_cmp_gt_f32_e32 vcc, s39, v68
	v_cvt_pk_bf16_f32 v65, v70, v71
	v_cvt_pk_bf16_f32 v66, v72, v73
	v_cndmask_b32_e32 v68, v68, v69, vcc
	v_rsq_f32_e32 v70, v68
	v_mad_i64_i32 v[68:69], s[8:9], v76, s40, v[146:147]
	v_cvt_pk_bf16_f32 v67, v74, v75
	v_mul_f32_e32 v71, 0x45800000, v70
	v_cndmask_b32_e32 v70, v70, v71, vcc
	v_pk_mul_f32 v[60:61], v[60:61], v[70:71] op_sel_hi:[1,0]
	v_lshl_add_u64 v[68:69], v[68:69], 0, v[148:149]
	v_mul_f32_e32 v71, 0xbfb8aa3b, v60
	v_exp_f32_e32 v71, v71
	v_mul_f32_e32 v72, 0xbfb8aa3b, v61
	v_exp_f32_e32 v72, v72
	ds_bpermute_b32 v206, v216, v68
	ds_bpermute_b32 v207, v216, v69
	ds_bpermute_b32 v212, v216, v64
	ds_bpermute_b32 v213, v216, v65
	ds_bpermute_b32 v214, v216, v66
	ds_bpermute_b32 v215, v216, v67
	s_waitcnt lgkmcnt(6)
; DI float sigmoidf_(float v) { return __builtin_amdgcn_rcpf(1.f + __builtin_amdgcn_exp2f(-v * 1.4426950408889634f)); }
; DI u32x4 pack8(f32x4 a, f32x4 b) { u32x4 w; w.x = cvtpk(a[0], a[1]); w.y = cvtpk(a[2], a[3]); w.z = cvtpk(b[0], b[1]); w.w = cvtpk(b[2], b[3]); return w; }
;   DI void operator()(const f32x4 (&acc)[2][2][4][2], const Unit& u, int wr, int wc, int fr, int fq) const {
;     const int row0 = u.pm * 256 + wr * 64 + fr; const int hcol = u.pn * 128 + wc * 32 + 8 * fq;
;     float rs[8];
; #pragma unroll
;     for (int i = 0; i < 8; ++i) rs[i] = ssq[row0 + (i >> 2) * 128 + (i & 3) * 16];
; #pragma unroll
;     for (int ai = 0; ai < 2; ++ai)
; #pragma unroll
;       for (int m = 0; m < 4; ++m) {
;         const int row = row0 + ai * 128 + m * 16;
;         const float rstd = rsqrtf(rs[ai * 4 + m] * (1.f / DM) + EPSN);
;         f32x4 o[2];
; #pragma unroll
;         for (int n = 0; n < 2; ++n) {
;           const f32x4 a = acc[ai][0][m][n] * rstd, b = acc[ai][1][m][n] * rstd;
; #pragma unroll
;           for (int e = 0; e < 4; ++e) o[n][e] = a[e] * sigmoidf_(a[e]) * b[e];
;         }
;         __builtin_nontemporal_store(pack8(o[0], o[1]), (u32x4*)(H + (size_t)row * DFF + hcol));
;       }
	global_store_dwordx4 v[204:205], v[208:211], off nt
	v_pk_mul_f32 v[62:63], v[62:63], v[70:71] op_sel_hi:[1,0]
	v_pk_mul_f32 v[52:53], v[52:53], v[70:71] op_sel_hi:[1,0]
	v_mul_f32_e32 v66, 0xbfb8aa3b, v62
	v_mul_f32_e32 v67, 0xbfb8aa3b, v63
	v_exp_f32_e32 v66, v66
	v_exp_f32_e32 v67, v67
	v_add_f32_e32 v64, 1.0, v71
	v_add_f32_e32 v65, 1.0, v72
	v_rcp_f32_e32 v64, v64
	v_rcp_f32_e32 v65, v65
	v_add_f32_e32 v66, 1.0, v66
	v_add_f32_e32 v67, 1.0, v67
	v_rcp_f32_e32 v66, v66
	v_rcp_f32_e32 v67, v67
	v_pk_mul_f32 v[60:61], v[60:61], v[64:65]
	v_pk_mul_f32 v[56:57], v[56:57], v[70:71] op_sel_hi:[1,0]
	v_pk_mul_f32 v[52:53], v[52:53], v[60:61]
	v_pk_mul_f32 v[60:61], v[62:63], v[66:67]
	v_mul_f32_e32 v62, 0xbfb8aa3b, v56
	v_mul_f32_e32 v63, 0xbfb8aa3b, v57
	v_exp_f32_e32 v62, v62
	v_exp_f32_e32 v63, v63
	v_pk_mul_f32 v[54:55], v[54:55], v[70:71] op_sel_hi:[1,0]
	v_pk_mul_f32 v[58:59], v[58:59], v[70:71] op_sel_hi:[1,0]
	v_pk_mul_f32 v[54:55], v[54:55], v[60:61]
	v_add_f32_e32 v60, 1.0, v62
	v_add_f32_e32 v61, 1.0, v63
	v_mul_f32_e32 v62, 0xbfb8aa3b, v58
	v_mul_f32_e32 v63, 0xbfb8aa3b, v59
	v_exp_f32_e32 v62, v62
	v_exp_f32_e32 v63, v63
	v_rcp_f32_e32 v60, v60
	v_rcp_f32_e32 v61, v61
	v_add_f32_e32 v62, 1.0, v62
	v_add_f32_e32 v63, 1.0, v63
	v_rcp_f32_e32 v62, v62
	v_rcp_f32_e32 v63, v63
	v_pk_mul_f32 v[56:57], v[56:57], v[60:61]
	v_pk_mul_f32 v[48:49], v[48:49], v[70:71] op_sel_hi:[1,0]
	v_pk_mul_f32 v[50:51], v[50:51], v[70:71] op_sel_hi:[1,0]
	v_pk_mul_f32 v[56:57], v[48:49], v[56:57]
	v_pk_mul_f32 v[48:49], v[58:59], v[62:63]
	s_nop 0
	v_pk_mul_f32 v[58:59], v[50:51], v[48:49]
	v_cvt_pk_bf16_f32 v48, v52, v53
	v_fmamk_f32 v52, v178, 0x3a800000, v156
	v_mul_f32_e32 v53, 0x4b800000, v52
	v_cmp_gt_f32_e32 vcc, s39, v52
	v_cvt_pk_bf16_f32 v49, v54, v55
	v_cvt_pk_bf16_f32 v50, v56, v57
	v_cndmask_b32_e32 v52, v52, v53, vcc
	v_rsq_f32_e32 v54, v52
	v_mad_i64_i32 v[52:53], s[8:9], v174, s40, v[146:147]
	v_cvt_pk_bf16_f32 v51, v58, v59
	v_mul_f32_e32 v55, 0x45800000, v54
	v_cndmask_b32_e32 v54, v54, v55, vcc
	v_pk_mul_f32 v[44:45], v[44:45], v[54:55] op_sel_hi:[1,0]
	v_lshl_add_u64 v[52:53], v[52:53], 0, v[148:149]
	v_mul_f32_e32 v55, 0xbfb8aa3b, v44
	v_exp_f32_e32 v55, v55
	v_mul_f32_e32 v56, 0xbfb8aa3b, v45
	v_exp_f32_e32 v56, v56
	ds_bpermute_b32 v204, v216, v52
	ds_bpermute_b32 v205, v216, v53
	ds_bpermute_b32 v208, v216, v48
	ds_bpermute_b32 v209, v216, v49
	ds_bpermute_b32 v210, v216, v50
	ds_bpermute_b32 v211, v216, v51
	s_waitcnt lgkmcnt(6)
	global_store_dwordx4 v[206:207], v[212:215], off nt
	v_pk_mul_f32 v[46:47], v[46:47], v[54:55] op_sel_hi:[1,0]
	v_pk_mul_f32 v[36:37], v[36:37], v[54:55] op_sel_hi:[1,0]
	v_mul_f32_e32 v50, 0xbfb8aa3b, v46
	v_mul_f32_e32 v51, 0xbfb8aa3b, v47
	v_exp_f32_e32 v50, v50
	v_exp_f32_e32 v51, v51
	v_add_f32_e32 v48, 1.0, v55
	v_add_f32_e32 v49, 1.0, v56
	v_rcp_f32_e32 v48, v48
	v_rcp_f32_e32 v49, v49
	v_add_f32_e32 v50, 1.0, v50
	v_add_f32_e32 v51, 1.0, v51
	v_rcp_f32_e32 v50, v50
	v_rcp_f32_e32 v51, v51
	v_pk_mul_f32 v[44:45], v[44:45], v[48:49]
	v_pk_mul_f32 v[40:41], v[40:41], v[54:55] op_sel_hi:[1,0]
	v_pk_mul_f32 v[36:37], v[36:37], v[44:45]
	v_pk_mul_f32 v[44:45], v[46:47], v[50:51]
	v_mul_f32_e32 v46, 0xbfb8aa3b, v40
	v_mul_f32_e32 v47, 0xbfb8aa3b, v41
	v_exp_f32_e32 v46, v46
	v_exp_f32_e32 v47, v47
	v_pk_mul_f32 v[38:39], v[38:39], v[54:55] op_sel_hi:[1,0]
	v_pk_mul_f32 v[42:43], v[42:43], v[54:55] op_sel_hi:[1,0]
	v_pk_mul_f32 v[38:39], v[38:39], v[44:45]
	v_add_f32_e32 v44, 1.0, v46
	v_add_f32_e32 v45, 1.0, v47
	v_mul_f32_e32 v46, 0xbfb8aa3b, v42
	v_mul_f32_e32 v47, 0xbfb8aa3b, v43
	v_exp_f32_e32 v46, v46
	v_exp_f32_e32 v47, v47
	v_rcp_f32_e32 v44, v44
	v_rcp_f32_e32 v45, v45
	v_add_f32_e32 v46, 1.0, v46
	v_add_f32_e32 v47, 1.0, v47
	v_rcp_f32_e32 v46, v46
	v_rcp_f32_e32 v47, v47
	v_pk_mul_f32 v[40:41], v[40:41], v[44:45]
	v_pk_mul_f32 v[32:33], v[32:33], v[54:55] op_sel_hi:[1,0]
	v_pk_mul_f32 v[34:35], v[34:35], v[54:55] op_sel_hi:[1,0]
	v_pk_mul_f32 v[40:41], v[32:33], v[40:41]
	v_pk_mul_f32 v[32:33], v[42:43], v[46:47]
	v_add_u32_e32 v44, 0x90, v144
	v_pk_mul_f32 v[42:43], v[34:35], v[32:33]
	v_cvt_pk_bf16_f32 v32, v36, v37
	v_fmamk_f32 v36, v157, 0x3a800000, v156
	v_mul_f32_e32 v37, 0x4b800000, v36
	v_cmp_gt_f32_e32 vcc, s39, v36
	v_cvt_pk_bf16_f32 v33, v38, v39
	v_cvt_pk_bf16_f32 v34, v40, v41
	v_cndmask_b32_e32 v36, v36, v37, vcc
	v_rsq_f32_e32 v38, v36
	v_mad_i64_i32 v[36:37], s[8:9], v44, s40, v[146:147]
	v_cvt_pk_bf16_f32 v35, v42, v43
	v_mul_f32_e32 v39, 0x45800000, v38
	v_cndmask_b32_e32 v38, v38, v39, vcc
	v_pk_mul_f32 v[28:29], v[28:29], v[38:39] op_sel_hi:[1,0]
	v_lshl_add_u64 v[36:37], v[36:37], 0, v[148:149]
	v_mul_f32_e32 v39, 0xbfb8aa3b, v28
	v_exp_f32_e32 v39, v39
	v_mul_f32_e32 v40, 0xbfb8aa3b, v29
	v_exp_f32_e32 v40, v40
	ds_bpermute_b32 v206, v216, v36
	ds_bpermute_b32 v207, v216, v37
	ds_bpermute_b32 v212, v216, v32
	ds_bpermute_b32 v213, v216, v33
	ds_bpermute_b32 v214, v216, v34
	ds_bpermute_b32 v215, v216, v35
	s_waitcnt lgkmcnt(6)
; DI float sigmoidf_(float v) { return __builtin_amdgcn_rcpf(1.f + __builtin_amdgcn_exp2f(-v * 1.4426950408889634f)); }
; DI u32x4 pack8(f32x4 a, f32x4 b) { u32x4 w; w.x = cvtpk(a[0], a[1]); w.y = cvtpk(a[2], a[3]); w.z = cvtpk(b[0], b[1]); w.w = cvtpk(b[2], b[3]); return w; }
;   DI void operator()(const f32x4 (&acc)[2][2][4][2], const Unit& u, int wr, int wc, int fr, int fq) const {
;     const int row0 = u.pm * 256 + wr * 64 + fr; const int hcol = u.pn * 128 + wc * 32 + 8 * fq;
;     float rs[8];
; #pragma unroll
;     for (int i = 0; i < 8; ++i) rs[i] = ssq[row0 + (i >> 2) * 128 + (i & 3) * 16];
; #pragma unroll
;     for (int ai = 0; ai < 2; ++ai)
; #pragma unroll
;       for (int m = 0; m < 4; ++m) {
;         const int row = row0 + ai * 128 + m * 16;
;         const float rstd = rsqrtf(rs[ai * 4 + m] * (1.f / DM) + EPSN);
;         f32x4 o[2];
; #pragma unroll
;         for (int n = 0; n < 2; ++n) {
;           const f32x4 a = acc[ai][0][m][n] * rstd, b = acc[ai][1][m][n] * rstd;
; #pragma unroll
;           for (int e = 0; e < 4; ++e) o[n][e] = a[e] * sigmoidf_(a[e]) * b[e];
;         }
;         __builtin_nontemporal_store(pack8(o[0], o[1]), (u32x4*)(H + (size_t)row * DFF + hcol));
;       }
	global_store_dwordx4 v[204:205], v[208:211], off nt
	v_pk_mul_f32 v[30:31], v[30:31], v[38:39] op_sel_hi:[1,0]
	v_pk_mul_f32 v[20:21], v[20:21], v[38:39] op_sel_hi:[1,0]
	v_mul_f32_e32 v34, 0xbfb8aa3b, v30
	v_mul_f32_e32 v35, 0xbfb8aa3b, v31
	v_exp_f32_e32 v34, v34
	v_exp_f32_e32 v35, v35
	v_add_f32_e32 v32, 1.0, v39
	v_add_f32_e32 v33, 1.0, v40
	v_rcp_f32_e32 v32, v32
	v_rcp_f32_e32 v33, v33
	v_add_f32_e32 v34, 1.0, v34
	v_add_f32_e32 v35, 1.0, v35
	v_rcp_f32_e32 v34, v34
	v_rcp_f32_e32 v35, v35
	v_pk_mul_f32 v[28:29], v[28:29], v[32:33]
	v_pk_mul_f32 v[24:25], v[24:25], v[38:39] op_sel_hi:[1,0]
	v_pk_mul_f32 v[20:21], v[20:21], v[28:29]
	v_pk_mul_f32 v[28:29], v[30:31], v[34:35]
	v_mul_f32_e32 v30, 0xbfb8aa3b, v24
	v_mul_f32_e32 v31, 0xbfb8aa3b, v25
	v_exp_f32_e32 v30, v30
	v_exp_f32_e32 v31, v31
	v_pk_mul_f32 v[22:23], v[22:23], v[38:39] op_sel_hi:[1,0]
	v_pk_mul_f32 v[26:27], v[26:27], v[38:39] op_sel_hi:[1,0]
	v_pk_mul_f32 v[22:23], v[22:23], v[28:29]
	v_add_f32_e32 v28, 1.0, v30
	v_add_f32_e32 v29, 1.0, v31
	v_mul_f32_e32 v30, 0xbfb8aa3b, v26
	v_mul_f32_e32 v31, 0xbfb8aa3b, v27
	v_exp_f32_e32 v30, v30
	v_exp_f32_e32 v31, v31
	v_rcp_f32_e32 v28, v28
	v_rcp_f32_e32 v29, v29
	v_add_f32_e32 v30, 1.0, v30
	v_add_f32_e32 v31, 1.0, v31
	v_rcp_f32_e32 v30, v30
	v_rcp_f32_e32 v31, v31
	v_pk_mul_f32 v[24:25], v[24:25], v[28:29]
	v_pk_mul_f32 v[16:17], v[16:17], v[38:39] op_sel_hi:[1,0]
	v_pk_mul_f32 v[18:19], v[18:19], v[38:39] op_sel_hi:[1,0]
	v_pk_mul_f32 v[24:25], v[16:17], v[24:25]
	v_pk_mul_f32 v[16:17], v[26:27], v[30:31]
	v_add_u32_e32 v28, 0xa0, v144
	v_pk_mul_f32 v[26:27], v[18:19], v[16:17]
	v_cvt_pk_bf16_f32 v16, v20, v21
	v_fmamk_f32 v20, v145, 0x3a800000, v156
	v_mul_f32_e32 v21, 0x4b800000, v20
	v_cmp_gt_f32_e32 vcc, s39, v20
	v_cvt_pk_bf16_f32 v17, v22, v23
	v_cvt_pk_bf16_f32 v18, v24, v25
	v_cndmask_b32_e32 v20, v20, v21, vcc
	v_rsq_f32_e32 v22, v20
	v_mad_i64_i32 v[20:21], s[8:9], v28, s40, v[146:147]
	v_cvt_pk_bf16_f32 v19, v26, v27
	v_mul_f32_e32 v23, 0x45800000, v22
	v_cndmask_b32_e32 v22, v22, v23, vcc
	v_pk_mul_f32 v[12:13], v[12:13], v[22:23] op_sel_hi:[1,0]
	v_lshl_add_u64 v[20:21], v[20:21], 0, v[148:149]
	v_mul_f32_e32 v23, 0xbfb8aa3b, v12
	v_exp_f32_e32 v23, v23
	v_mul_f32_e32 v24, 0xbfb8aa3b, v13
	v_exp_f32_e32 v24, v24
	ds_bpermute_b32 v204, v216, v20
	ds_bpermute_b32 v205, v216, v21
	ds_bpermute_b32 v208, v216, v16
	ds_bpermute_b32 v209, v216, v17
	ds_bpermute_b32 v210, v216, v18
	ds_bpermute_b32 v211, v216, v19
	s_waitcnt lgkmcnt(6)
	global_store_dwordx4 v[206:207], v[212:215], off nt
	v_pk_mul_f32 v[14:15], v[14:15], v[22:23] op_sel_hi:[1,0]
	v_pk_mul_f32 v[4:5], v[4:5], v[22:23] op_sel_hi:[1,0]
	v_mul_f32_e32 v18, 0xbfb8aa3b, v14
	v_mul_f32_e32 v19, 0xbfb8aa3b, v15
	v_exp_f32_e32 v18, v18
	v_exp_f32_e32 v19, v19
	v_add_f32_e32 v16, 1.0, v23
	v_add_f32_e32 v17, 1.0, v24
	v_rcp_f32_e32 v16, v16
	v_rcp_f32_e32 v17, v17
	v_add_f32_e32 v18, 1.0, v18
	v_add_f32_e32 v19, 1.0, v19
	v_rcp_f32_e32 v18, v18
	v_rcp_f32_e32 v19, v19
	v_pk_mul_f32 v[12:13], v[12:13], v[16:17]
	v_pk_mul_f32 v[8:9], v[8:9], v[22:23] op_sel_hi:[1,0]
	v_pk_mul_f32 v[4:5], v[4:5], v[12:13]
	v_pk_mul_f32 v[12:13], v[14:15], v[18:19]
	v_mul_f32_e32 v14, 0xbfb8aa3b, v8
	v_mul_f32_e32 v15, 0xbfb8aa3b, v9
	v_exp_f32_e32 v14, v14
	v_exp_f32_e32 v15, v15
	v_pk_mul_f32 v[6:7], v[6:7], v[22:23] op_sel_hi:[1,0]
	v_pk_mul_f32 v[10:11], v[10:11], v[22:23] op_sel_hi:[1,0]
	v_pk_mul_f32 v[6:7], v[6:7], v[12:13]
	v_add_f32_e32 v12, 1.0, v14
	v_add_f32_e32 v13, 1.0, v15
	v_mul_f32_e32 v14, 0xbfb8aa3b, v10
	v_mul_f32_e32 v15, 0xbfb8aa3b, v11
	v_exp_f32_e32 v14, v14
	v_exp_f32_e32 v15, v15
	v_rcp_f32_e32 v12, v12
	v_rcp_f32_e32 v13, v13
	v_add_f32_e32 v14, 1.0, v14
	v_add_f32_e32 v15, 1.0, v15
	v_rcp_f32_e32 v14, v14
	v_rcp_f32_e32 v15, v15
	v_pk_mul_f32 v[8:9], v[8:9], v[12:13]
	v_pk_mul_f32 v[0:1], v[0:1], v[22:23] op_sel_hi:[1,0]
	v_pk_mul_f32 v[2:3], v[2:3], v[22:23] op_sel_hi:[1,0]
	v_pk_mul_f32 v[8:9], v[0:1], v[8:9]
	v_pk_mul_f32 v[0:1], v[10:11], v[14:15]
	v_add_u32_e32 v12, 0xb0, v144
	v_pk_mul_f32 v[10:11], v[2:3], v[0:1]
	v_cvt_pk_bf16_f32 v0, v4, v5
	v_mad_i64_i32 v[4:5], s[8:9], v12, s40, v[146:147]
	v_cvt_pk_bf16_f32 v1, v6, v7
	v_cvt_pk_bf16_f32 v2, v8, v9
	v_cvt_pk_bf16_f32 v3, v10, v11
	v_lshl_add_u64 v[4:5], v[4:5], 0, v[148:149]
	s_andn2_b64 vcc, exec, s[6:7]
	s_mov_b64 s[6:7], -1
	ds_bpermute_b32 v206, v216, v4
	ds_bpermute_b32 v207, v216, v5
	ds_bpermute_b32 v212, v216, v0
	ds_bpermute_b32 v213, v216, v1
	ds_bpermute_b32 v214, v216, v2
	ds_bpermute_b32 v215, v216, v3
	s_waitcnt lgkmcnt(6)
	global_store_dwordx4 v[204:205], v[208:211], off nt
	s_waitcnt lgkmcnt(0)
	global_store_dwordx4 v[206:207], v[212:215], off nt
	s_cbranch_vccnz .LBB0_448
	s_andn2_b64 vcc, exec, s[0:1]
	s_cbranch_vccnz .LBB0_447
	s_barrier
	s_branch .LBB0_447

; DI float sigmoidf_(float v) { return __builtin_amdgcn_rcpf(1.f + __builtin_amdgcn_exp2f(-v * 1.4426950408889634f)); }
; DI u32x4 pack8(f32x4 a, f32x4 b) { u32x4 w; w.x = cvtpk(a[0], a[1]); w.y = cvtpk(a[2], a[3]); w.z = cvtpk(b[0], b[1]); w.w = cvtpk(b[2], b[3]); return w; }
;   DI void operator()(const f32x4 (&acc)[2][2][4][2], const Unit& u, int wr, int wc, int fr, int fq) const {
;     const int row0 = u.pm * 256 + wr * 64 + fr; const int hcol = u.pn * 128 + wc * 32 + 8 * fq;
;     float rs[8];
; #pragma unroll
;     for (int i = 0; i < 8; ++i) rs[i] = ssq[row0 + (i >> 2) * 128 + (i & 3) * 16];
; #pragma unroll
;     for (int ai = 0; ai < 2; ++ai)
; #pragma unroll
;       for (int m = 0; m < 4; ++m) {
;         const int row = row0 + ai * 128 + m * 16;
;         const float rstd = rsqrtf(rs[ai * 4 + m] * (1.f / DM) + EPSN);
;         f32x4 o[2];
; #pragma unroll
;         for (int n = 0; n < 2; ++n) {
;           const f32x4 a = acc[ai][0][m][n] * rstd, b = acc[ai][1][m][n] * rstd;
; #pragma unroll
;           for (int e = 0; e < 4; ++e) o[n][e] = a[e] * sigmoidf_(a[e]) * b[e];
;         }
;         __builtin_nontemporal_store(pack8(o[0], o[1]), (u32x4*)(H + (size_t)row * DFF + hcol));
;       }
.LBB0_1256:
	v_and_b32_e32 v216, 63, v200
	v_lshrrev_b32_e32 v217, 2, v216
	v_and_b32_e32 v216, 3, v216
	v_lshl_add_u32 v216, v216, 4, v217
	v_lshlrev_b32_e32 v216, 2, v216
	v_lshl_add_u32 v144, s10, 8, v150
	v_ashrrev_i32_e32 v145, 31, v144
	v_lshl_add_u64 v[148:149], v[144:145], 2, s[66:67]
	global_load_dword v162, v[148:149], off
	global_load_dword v163, v[148:149], off offset:64
	global_load_dword v175, v[148:149], off offset:128
	global_load_dword v176, v[148:149], off offset:192
	global_load_dword v177, v[148:149], off offset:512
	global_load_dword v178, v[148:149], off offset:576
	global_load_dword v157, v[148:149], off offset:640
	global_load_dword v145, v[148:149], off offset:704
	v_lshl_or_b32 v158, s11, 7, v152
	v_readlane_b32 s10, v252, 3
	v_readlane_b32 s11, v252, 4
	v_ashrrev_i32_e32 v159, 31, v158
	v_add_u32_e32 v174, 0x80, v144
	v_mov_b64_e32 v[146:147], s[10:11]
	v_mad_i64_i32 v[160:161], s[10:11], v144, s39, v[146:147]
	s_waitcnt vmcnt(0)
	v_fmamk_f32 v148, v162, 0x3a800000, v156
	v_fmamk_f32 v149, v163, 0x3a800000, v156
	v_mul_f32_e32 v162, 0x4b800000, v148
	v_cmp_gt_f32_e32 vcc, s38, v148
	v_mul_f32_e32 v163, 0x4b800000, v149
	v_cmp_gt_f32_e64 s[10:11], s38, v149
	v_cndmask_b32_e32 v148, v148, v162, vcc
	v_rsq_f32_e32 v162, v148
	v_cndmask_b32_e64 v149, v149, v163, s[10:11]
	v_rsq_f32_e32 v163, v149
	v_lshlrev_b64 v[148:149], 1, v[158:159]
	v_lshl_add_u64 v[158:159], v[160:161], 0, v[148:149]
	v_mul_f32_e32 v160, 0x45800000, v162
	v_mul_f32_e32 v161, 0x45800000, v163
	v_cndmask_b32_e32 v160, v162, v160, vcc
	v_cndmask_b32_e64 v162, v163, v161, s[10:11]
	v_pk_mul_f32 v[124:125], v[124:125], v[160:161] op_sel_hi:[1,0]
	v_pk_mul_f32 v[126:127], v[126:127], v[160:161] op_sel_hi:[1,0]
	v_pk_mul_f32 v[120:121], v[120:121], v[160:161] op_sel_hi:[1,0]
	v_pk_mul_f32 v[122:123], v[122:123], v[160:161] op_sel_hi:[1,0]
	v_pk_mul_f32 v[112:113], v[112:113], v[160:161] op_sel_hi:[1,0]
	v_pk_mul_f32 v[114:115], v[114:115], v[160:161] op_sel_hi:[1,0]
	v_pk_mul_f32 v[108:109], v[108:109], v[160:161] op_sel_hi:[1,0]
	v_pk_mul_f32 v[110:111], v[110:111], v[160:161] op_sel_hi:[1,0]
	v_pk_mul_f32 v[116:117], v[116:117], v[162:163] op_sel_hi:[1,0]
	v_pk_mul_f32 v[100:101], v[100:101], v[162:163] op_sel_hi:[1,0]
	v_pk_mul_f32 v[118:119], v[118:119], v[162:163] op_sel_hi:[1,0]
	v_mul_f32_e32 v160, 0xbfb8aa3b, v124
	v_mul_f32_e32 v161, 0xbfb8aa3b, v125
	v_mul_f32_e32 v163, 0xbfb8aa3b, v126
	v_mul_f32_e32 v164, 0xbfb8aa3b, v127
	v_mul_f32_e32 v165, 0xbfb8aa3b, v120
	v_mul_f32_e32 v166, 0xbfb8aa3b, v121
	v_mul_f32_e32 v167, 0xbfb8aa3b, v122
	v_mul_f32_e32 v168, 0xbfb8aa3b, v123
	v_mul_f32_e32 v169, 0xbfb8aa3b, v116
	v_exp_f32_e32 v160, v160
	v_exp_f32_e32 v161, v161
	v_exp_f32_e32 v163, v163
	v_exp_f32_e32 v164, v164
	v_exp_f32_e32 v165, v165
	v_exp_f32_e32 v166, v166
	v_exp_f32_e32 v167, v167
	v_exp_f32_e32 v168, v168
	v_exp_f32_e32 v169, v169
	v_add_f32_e32 v160, 1.0, v160
	v_add_f32_e32 v161, 1.0, v161
	v_add_f32_e32 v163, 1.0, v163
	v_add_f32_e32 v173, 1.0, v164
	v_add_f32_e32 v179, 1.0, v165
	v_add_f32_e32 v180, 1.0, v166
	v_add_f32_e32 v181, 1.0, v167
	v_add_f32_e32 v182, 1.0, v168
	v_add_f32_e32 v183, 1.0, v169
	v_rcp_f32_e32 v160, v160
	v_rcp_f32_e32 v161, v161
	v_rcp_f32_e32 v164, v163
	v_rcp_f32_e32 v165, v173
	v_rcp_f32_e32 v166, v179
	v_rcp_f32_e32 v167, v180
	v_rcp_f32_e32 v168, v181
	v_rcp_f32_e32 v169, v182
	v_mul_f32_e32 v171, 0xbfb8aa3b, v118
	v_mul_f32_e32 v172, 0xbfb8aa3b, v119
	v_exp_f32_e32 v171, v171
	v_exp_f32_e32 v172, v172
	v_pk_mul_f32 v[124:125], v[124:125], v[160:161]
	v_pk_mul_f32 v[126:127], v[126:127], v[164:165]
	v_pk_mul_f32 v[120:121], v[120:121], v[166:167]
	v_pk_mul_f32 v[122:123], v[122:123], v[168:169]
	v_pk_mul_f32 v[112:113], v[112:113], v[124:125]
	v_pk_mul_f32 v[114:115], v[114:115], v[126:127]
	v_pk_mul_f32 v[120:121], v[108:109], v[120:121]
	v_pk_mul_f32 v[122:123], v[110:111], v[122:123]
	v_add_f32_e32 v185, 1.0, v171
	v_add_f32_e32 v186, 1.0, v172
	v_cvt_pk_bf16_f32 v108, v112, v113
	v_cvt_pk_bf16_f32 v109, v114, v115
	v_cvt_pk_bf16_f32 v110, v120, v121
	v_cvt_pk_bf16_f32 v111, v122, v123
	v_pk_mul_f32 v[104:105], v[104:105], v[162:163] op_sel_hi:[1,0]
	v_rcp_f32_e32 v172, v185
	v_rcp_f32_e32 v173, v186
	ds_bpermute_b32 v204, v216, v158
	ds_bpermute_b32 v205, v216, v159
	ds_bpermute_b32 v208, v216, v108
	ds_bpermute_b32 v209, v216, v109
	ds_bpermute_b32 v210, v216, v110
	ds_bpermute_b32 v211, v216, v111
	v_mul_f32_e32 v170, 0xbfb8aa3b, v117
	v_pk_mul_f32 v[102:103], v[102:103], v[162:163] op_sel_hi:[1,0]
	v_mul_f32_e32 v110, 0xbfb8aa3b, v104
	v_mul_f32_e32 v111, 0xbfb8aa3b, v105
	v_exp_f32_e32 v110, v110
	v_exp_f32_e32 v111, v111
	v_pk_mul_f32 v[108:109], v[118:119], v[172:173]
	v_pk_mul_f32 v[106:107], v[106:107], v[162:163] op_sel_hi:[1,0]
	v_exp_f32_e32 v170, v170
	v_pk_mul_f32 v[102:103], v[102:103], v[108:109]
	v_add_f32_e32 v108, 1.0, v110
	v_add_f32_e32 v109, 1.0, v111
	v_mul_f32_e32 v110, 0xbfb8aa3b, v106
	v_mul_f32_e32 v111, 0xbfb8aa3b, v107
	v_exp_f32_e32 v110, v110
	v_exp_f32_e32 v111, v111
	v_add_f32_e32 v184, 1.0, v170
	v_rcp_f32_e32 v170, v183
	v_rcp_f32_e32 v171, v184
	v_rcp_f32_e32 v108, v108
	v_rcp_f32_e32 v109, v109
	v_add_f32_e32 v110, 1.0, v110
	v_add_f32_e32 v111, 1.0, v111
	v_rcp_f32_e32 v110, v110
	v_rcp_f32_e32 v111, v111
	v_pk_mul_f32 v[116:117], v[116:117], v[170:171]
	v_pk_mul_f32 v[104:105], v[104:105], v[108:109]
	v_pk_mul_f32 v[96:97], v[96:97], v[162:163] op_sel_hi:[1,0]
	v_pk_mul_f32 v[100:101], v[100:101], v[116:117]
	v_pk_mul_f32 v[104:105], v[96:97], v[104:105]
	v_pk_mul_f32 v[96:97], v[106:107], v[110:111]
	v_pk_mul_f32 v[98:99], v[98:99], v[162:163] op_sel_hi:[1,0]
	v_or_b32_e32 v108, 16, v144
	v_pk_mul_f32 v[106:107], v[98:99], v[96:97]
	v_cvt_pk_bf16_f32 v96, v100, v101
	v_fmamk_f32 v100, v175, 0x3a800000, v156
	v_mul_f32_e32 v101, 0x4b800000, v100
	v_cmp_gt_f32_e32 vcc, s38, v100
	v_cvt_pk_bf16_f32 v97, v102, v103
	v_cvt_pk_bf16_f32 v98, v104, v105
	v_cndmask_b32_e32 v100, v100, v101, vcc
	v_rsq_f32_e32 v102, v100
	v_mad_i64_i32 v[100:101], s[10:11], v108, s39, v[146:147]
	v_cvt_pk_bf16_f32 v99, v106, v107
	v_mul_f32_e32 v103, 0x45800000, v102
	v_cndmask_b32_e32 v102, v102, v103, vcc
	v_pk_mul_f32 v[92:93], v[92:93], v[102:103] op_sel_hi:[1,0]
	v_lshl_add_u64 v[100:101], v[100:101], 0, v[148:149]
	v_mul_f32_e32 v103, 0xbfb8aa3b, v92
	v_exp_f32_e32 v103, v103
	v_mul_f32_e32 v104, 0xbfb8aa3b, v93
	v_exp_f32_e32 v104, v104
	ds_bpermute_b32 v206, v216, v100
	ds_bpermute_b32 v207, v216, v101
	ds_bpermute_b32 v212, v216, v96
	ds_bpermute_b32 v213, v216, v97
	ds_bpermute_b32 v214, v216, v98
	ds_bpermute_b32 v215, v216, v99
	s_waitcnt lgkmcnt(6)
; DI float sigmoidf_(float v) { return __builtin_amdgcn_rcpf(1.f + __builtin_amdgcn_exp2f(-v * 1.4426950408889634f)); }
; DI u32x4 pack8(f32x4 a, f32x4 b) { u32x4 w; w.x = cvtpk(a[0], a[1]); w.y = cvtpk(a[2], a[3]); w.z = cvtpk(b[0], b[1]); w.w = cvtpk(b[2], b[3]); return w; }
;   DI void operator()(const f32x4 (&acc)[2][2][4][2], const Unit& u, int wr, int wc, int fr, int fq) const {
;     const int row0 = u.pm * 256 + wr * 64 + fr; const int hcol = u.pn * 128 + wc * 32 + 8 * fq;
;     float rs[8];
; #pragma unroll
;     for (int i = 0; i < 8; ++i) rs[i] = ssq[row0 + (i >> 2) * 128 + (i & 3) * 16];
; #pragma unroll
;     for (int ai = 0; ai < 2; ++ai)
; #pragma unroll
;       for (int m = 0; m < 4; ++m) {
;         const int row = row0 + ai * 128 + m * 16;
;         const float rstd = rsqrtf(rs[ai * 4 + m] * (1.f / DM) + EPSN);
;         f32x4 o[2];
; #pragma unroll
;         for (int n = 0; n < 2; ++n) {
;           const f32x4 a = acc[ai][0][m][n] * rstd, b = acc[ai][1][m][n] * rstd;
; #pragma unroll
;           for (int e = 0; e < 4; ++e) o[n][e] = a[e] * sigmoidf_(a[e]) * b[e];
;         }
;         __builtin_nontemporal_store(pack8(o[0], o[1]), (u32x4*)(H + (size_t)row * DFF + hcol));
;       }
	global_store_dwordx4 v[204:205], v[208:211], off nt
	v_pk_mul_f32 v[94:95], v[94:95], v[102:103] op_sel_hi:[1,0]
	v_pk_mul_f32 v[84:85], v[84:85], v[102:103] op_sel_hi:[1,0]
	v_mul_f32_e32 v98, 0xbfb8aa3b, v94
	v_mul_f32_e32 v99, 0xbfb8aa3b, v95
	v_exp_f32_e32 v98, v98
	v_exp_f32_e32 v99, v99
	v_add_f32_e32 v96, 1.0, v103
	v_add_f32_e32 v97, 1.0, v104
	v_rcp_f32_e32 v96, v96
	v_rcp_f32_e32 v97, v97
	v_add_f32_e32 v98, 1.0, v98
	v_add_f32_e32 v99, 1.0, v99
	v_rcp_f32_e32 v98, v98
	v_rcp_f32_e32 v99, v99
	v_pk_mul_f32 v[92:93], v[92:93], v[96:97]
	v_pk_mul_f32 v[88:89], v[88:89], v[102:103] op_sel_hi:[1,0]
	v_pk_mul_f32 v[84:85], v[84:85], v[92:93]
	v_pk_mul_f32 v[92:93], v[94:95], v[98:99]
	v_mul_f32_e32 v94, 0xbfb8aa3b, v88
	v_mul_f32_e32 v95, 0xbfb8aa3b, v89
	v_exp_f32_e32 v94, v94
	v_exp_f32_e32 v95, v95
	v_pk_mul_f32 v[86:87], v[86:87], v[102:103] op_sel_hi:[1,0]
	v_pk_mul_f32 v[90:91], v[90:91], v[102:103] op_sel_hi:[1,0]
	v_pk_mul_f32 v[86:87], v[86:87], v[92:93]
	v_add_f32_e32 v92, 1.0, v94
	v_add_f32_e32 v93, 1.0, v95
	v_mul_f32_e32 v94, 0xbfb8aa3b, v90
	v_mul_f32_e32 v95, 0xbfb8aa3b, v91
	v_exp_f32_e32 v94, v94
	v_exp_f32_e32 v95, v95
	v_rcp_f32_e32 v92, v92
	v_rcp_f32_e32 v93, v93
	v_add_f32_e32 v94, 1.0, v94
	v_add_f32_e32 v95, 1.0, v95
	v_rcp_f32_e32 v94, v94
	v_rcp_f32_e32 v95, v95
	v_pk_mul_f32 v[88:89], v[88:89], v[92:93]
	v_pk_mul_f32 v[80:81], v[80:81], v[102:103] op_sel_hi:[1,0]
	v_pk_mul_f32 v[82:83], v[82:83], v[102:103] op_sel_hi:[1,0]
	v_pk_mul_f32 v[88:89], v[80:81], v[88:89]
	v_pk_mul_f32 v[80:81], v[90:91], v[94:95]
	v_or_b32_e32 v92, 32, v144
	v_pk_mul_f32 v[90:91], v[82:83], v[80:81]
	v_cvt_pk_bf16_f32 v80, v84, v85
	v_fmamk_f32 v84, v176, 0x3a800000, v156
	v_mul_f32_e32 v85, 0x4b800000, v84
	v_cmp_gt_f32_e32 vcc, s38, v84
	v_cvt_pk_bf16_f32 v81, v86, v87
	v_cvt_pk_bf16_f32 v82, v88, v89
	v_cndmask_b32_e32 v84, v84, v85, vcc
	v_rsq_f32_e32 v86, v84
	v_mad_i64_i32 v[84:85], s[10:11], v92, s39, v[146:147]
	v_cvt_pk_bf16_f32 v83, v90, v91
	v_mul_f32_e32 v87, 0x45800000, v86
	v_cndmask_b32_e32 v86, v86, v87, vcc
	v_pk_mul_f32 v[76:77], v[76:77], v[86:87] op_sel_hi:[1,0]
	v_lshl_add_u64 v[84:85], v[84:85], 0, v[148:149]
	v_mul_f32_e32 v87, 0xbfb8aa3b, v76
	v_exp_f32_e32 v87, v87
	v_mul_f32_e32 v88, 0xbfb8aa3b, v77
	v_exp_f32_e32 v88, v88
	ds_bpermute_b32 v204, v216, v84
	ds_bpermute_b32 v205, v216, v85
	ds_bpermute_b32 v208, v216, v80
	ds_bpermute_b32 v209, v216, v81
	ds_bpermute_b32 v210, v216, v82
	ds_bpermute_b32 v211, v216, v83
	s_waitcnt lgkmcnt(6)
	global_store_dwordx4 v[206:207], v[212:215], off nt
	v_pk_mul_f32 v[78:79], v[78:79], v[86:87] op_sel_hi:[1,0]
	v_pk_mul_f32 v[68:69], v[68:69], v[86:87] op_sel_hi:[1,0]
	v_mul_f32_e32 v82, 0xbfb8aa3b, v78
	v_mul_f32_e32 v83, 0xbfb8aa3b, v79
	v_exp_f32_e32 v82, v82
	v_exp_f32_e32 v83, v83
	v_add_f32_e32 v80, 1.0, v87
	v_add_f32_e32 v81, 1.0, v88
	v_rcp_f32_e32 v80, v80
	v_rcp_f32_e32 v81, v81
	v_add_f32_e32 v82, 1.0, v82
	v_add_f32_e32 v83, 1.0, v83
	v_rcp_f32_e32 v82, v82
	v_rcp_f32_e32 v83, v83
	v_pk_mul_f32 v[76:77], v[76:77], v[80:81]
	v_pk_mul_f32 v[72:73], v[72:73], v[86:87] op_sel_hi:[1,0]
	v_pk_mul_f32 v[68:69], v[68:69], v[76:77]
	v_pk_mul_f32 v[76:77], v[78:79], v[82:83]
	v_mul_f32_e32 v78, 0xbfb8aa3b, v72
	v_mul_f32_e32 v79, 0xbfb8aa3b, v73
	v_exp_f32_e32 v78, v78
	v_exp_f32_e32 v79, v79
	v_pk_mul_f32 v[70:71], v[70:71], v[86:87] op_sel_hi:[1,0]
	v_pk_mul_f32 v[74:75], v[74:75], v[86:87] op_sel_hi:[1,0]
	v_pk_mul_f32 v[70:71], v[70:71], v[76:77]
	v_add_f32_e32 v76, 1.0, v78
	v_add_f32_e32 v77, 1.0, v79
	v_mul_f32_e32 v78, 0xbfb8aa3b, v74
	v_mul_f32_e32 v79, 0xbfb8aa3b, v75
	v_exp_f32_e32 v78, v78
	v_exp_f32_e32 v79, v79
	v_rcp_f32_e32 v76, v76
	v_rcp_f32_e32 v77, v77
	v_add_f32_e32 v78, 1.0, v78
	v_add_f32_e32 v79, 1.0, v79
	v_rcp_f32_e32 v78, v78
	v_rcp_f32_e32 v79, v79
	v_pk_mul_f32 v[72:73], v[72:73], v[76:77]
	v_pk_mul_f32 v[64:65], v[64:65], v[86:87] op_sel_hi:[1,0]
	v_pk_mul_f32 v[66:67], v[66:67], v[86:87] op_sel_hi:[1,0]
	v_pk_mul_f32 v[72:73], v[64:65], v[72:73]
	v_pk_mul_f32 v[64:65], v[74:75], v[78:79]
	v_or_b32_e32 v76, 48, v144
	v_pk_mul_f32 v[74:75], v[66:67], v[64:65]
	v_cvt_pk_bf16_f32 v64, v68, v69
	v_fmamk_f32 v68, v177, 0x3a800000, v156
	v_mul_f32_e32 v69, 0x4b800000, v68
	v_cmp_gt_f32_e32 vcc, s38, v68
	v_cvt_pk_bf16_f32 v65, v70, v71
	v_cvt_pk_bf16_f32 v66, v72, v73
	v_cndmask_b32_e32 v68, v68, v69, vcc
	v_rsq_f32_e32 v70, v68
	v_mad_i64_i32 v[68:69], s[10:11], v76, s39, v[146:147]
	v_cvt_pk_bf16_f32 v67, v74, v75
	v_mul_f32_e32 v71, 0x45800000, v70
	v_cndmask_b32_e32 v70, v70, v71, vcc
	v_pk_mul_f32 v[60:61], v[60:61], v[70:71] op_sel_hi:[1,0]
	v_lshl_add_u64 v[68:69], v[68:69], 0, v[148:149]
	v_mul_f32_e32 v71, 0xbfb8aa3b, v60
	v_exp_f32_e32 v71, v71
	v_mul_f32_e32 v72, 0xbfb8aa3b, v61
	v_exp_f32_e32 v72, v72
	ds_bpermute_b32 v206, v216, v68
	ds_bpermute_b32 v207, v216, v69
	ds_bpermute_b32 v212, v216, v64
	ds_bpermute_b32 v213, v216, v65
	ds_bpermute_b32 v214, v216, v66
	ds_bpermute_b32 v215, v216, v67
	s_waitcnt lgkmcnt(6)
; DI float sigmoidf_(float v) { return __builtin_amdgcn_rcpf(1.f + __builtin_amdgcn_exp2f(-v * 1.4426950408889634f)); }
; DI u32x4 pack8(f32x4 a, f32x4 b) { u32x4 w; w.x = cvtpk(a[0], a[1]); w.y = cvtpk(a[2], a[3]); w.z = cvtpk(b[0], b[1]); w.w = cvtpk(b[2], b[3]); return w; }
;   DI void operator()(const f32x4 (&acc)[2][2][4][2], const Unit& u, int wr, int wc, int fr, int fq) const {
;     const int row0 = u.pm * 256 + wr * 64 + fr; const int hcol = u.pn * 128 + wc * 32 + 8 * fq;
;     float rs[8];
; #pragma unroll
;     for (int i = 0; i < 8; ++i) rs[i] = ssq[row0 + (i >> 2) * 128 + (i & 3) * 16];
; #pragma unroll
;     for (int ai = 0; ai < 2; ++ai)
; #pragma unroll
;       for (int m = 0; m < 4; ++m) {
;         const int row = row0 + ai * 128 + m * 16;
;         const float rstd = rsqrtf(rs[ai * 4 + m] * (1.f / DM) + EPSN);
;         f32x4 o[2];
; #pragma unroll
;         for (int n = 0; n < 2; ++n) {
;           const f32x4 a = acc[ai][0][m][n] * rstd, b = acc[ai][1][m][n] * rstd;
; #pragma unroll
;           for (int e = 0; e < 4; ++e) o[n][e] = a[e] * sigmoidf_(a[e]) * b[e];
;         }
;         __builtin_nontemporal_store(pack8(o[0], o[1]), (u32x4*)(H + (size_t)row * DFF + hcol));
;       }
	global_store_dwordx4 v[204:205], v[208:211], off nt
	v_pk_mul_f32 v[62:63], v[62:63], v[70:71] op_sel_hi:[1,0]
	v_pk_mul_f32 v[52:53], v[52:53], v[70:71] op_sel_hi:[1,0]
	v_mul_f32_e32 v66, 0xbfb8aa3b, v62
	v_mul_f32_e32 v67, 0xbfb8aa3b, v63
	v_exp_f32_e32 v66, v66
	v_exp_f32_e32 v67, v67
	v_add_f32_e32 v64, 1.0, v71
	v_add_f32_e32 v65, 1.0, v72
	v_rcp_f32_e32 v64, v64
	v_rcp_f32_e32 v65, v65
	v_add_f32_e32 v66, 1.0, v66
	v_add_f32_e32 v67, 1.0, v67
	v_rcp_f32_e32 v66, v66
	v_rcp_f32_e32 v67, v67
	v_pk_mul_f32 v[60:61], v[60:61], v[64:65]
	v_pk_mul_f32 v[56:57], v[56:57], v[70:71] op_sel_hi:[1,0]
	v_pk_mul_f32 v[52:53], v[52:53], v[60:61]
	v_pk_mul_f32 v[60:61], v[62:63], v[66:67]
	v_mul_f32_e32 v62, 0xbfb8aa3b, v56
	v_mul_f32_e32 v63, 0xbfb8aa3b, v57
	v_exp_f32_e32 v62, v62
	v_exp_f32_e32 v63, v63
	v_pk_mul_f32 v[54:55], v[54:55], v[70:71] op_sel_hi:[1,0]
	v_pk_mul_f32 v[58:59], v[58:59], v[70:71] op_sel_hi:[1,0]
	v_pk_mul_f32 v[54:55], v[54:55], v[60:61]
	v_add_f32_e32 v60, 1.0, v62
	v_add_f32_e32 v61, 1.0, v63
	v_mul_f32_e32 v62, 0xbfb8aa3b, v58
	v_mul_f32_e32 v63, 0xbfb8aa3b, v59
	v_exp_f32_e32 v62, v62
	v_exp_f32_e32 v63, v63
	v_rcp_f32_e32 v60, v60
	v_rcp_f32_e32 v61, v61
	v_add_f32_e32 v62, 1.0, v62
	v_add_f32_e32 v63, 1.0, v63
	v_rcp_f32_e32 v62, v62
	v_rcp_f32_e32 v63, v63
	v_pk_mul_f32 v[56:57], v[56:57], v[60:61]
	v_pk_mul_f32 v[48:49], v[48:49], v[70:71] op_sel_hi:[1,0]
	v_pk_mul_f32 v[50:51], v[50:51], v[70:71] op_sel_hi:[1,0]
	v_pk_mul_f32 v[56:57], v[48:49], v[56:57]
	v_pk_mul_f32 v[48:49], v[58:59], v[62:63]
	s_nop 0
	v_pk_mul_f32 v[58:59], v[50:51], v[48:49]
	v_cvt_pk_bf16_f32 v48, v52, v53
	v_fmamk_f32 v52, v178, 0x3a800000, v156
	v_mul_f32_e32 v53, 0x4b800000, v52
	v_cmp_gt_f32_e32 vcc, s38, v52
	v_cvt_pk_bf16_f32 v49, v54, v55
	v_cvt_pk_bf16_f32 v50, v56, v57
	v_cndmask_b32_e32 v52, v52, v53, vcc
	v_rsq_f32_e32 v54, v52
	v_mad_i64_i32 v[52:53], s[10:11], v174, s39, v[146:147]
	v_cvt_pk_bf16_f32 v51, v58, v59
	v_mul_f32_e32 v55, 0x45800000, v54
	v_cndmask_b32_e32 v54, v54, v55, vcc
	v_pk_mul_f32 v[44:45], v[44:45], v[54:55] op_sel_hi:[1,0]
	v_lshl_add_u64 v[52:53], v[52:53], 0, v[148:149]
	v_mul_f32_e32 v55, 0xbfb8aa3b, v44
	v_exp_f32_e32 v55, v55
	v_mul_f32_e32 v56, 0xbfb8aa3b, v45
	v_exp_f32_e32 v56, v56
	ds_bpermute_b32 v204, v216, v52
	ds_bpermute_b32 v205, v216, v53
	ds_bpermute_b32 v208, v216, v48
	ds_bpermute_b32 v209, v216, v49
	ds_bpermute_b32 v210, v216, v50
	ds_bpermute_b32 v211, v216, v51
	s_waitcnt lgkmcnt(6)
	global_store_dwordx4 v[206:207], v[212:215], off nt
	v_pk_mul_f32 v[46:47], v[46:47], v[54:55] op_sel_hi:[1,0]
	v_pk_mul_f32 v[36:37], v[36:37], v[54:55] op_sel_hi:[1,0]
	v_mul_f32_e32 v50, 0xbfb8aa3b, v46
	v_mul_f32_e32 v51, 0xbfb8aa3b, v47
	v_exp_f32_e32 v50, v50
	v_exp_f32_e32 v51, v51
	v_add_f32_e32 v48, 1.0, v55
	v_add_f32_e32 v49, 1.0, v56
	v_rcp_f32_e32 v48, v48
	v_rcp_f32_e32 v49, v49
	v_add_f32_e32 v50, 1.0, v50
	v_add_f32_e32 v51, 1.0, v51
	v_rcp_f32_e32 v50, v50
	v_rcp_f32_e32 v51, v51
	v_pk_mul_f32 v[44:45], v[44:45], v[48:49]
	v_pk_mul_f32 v[40:41], v[40:41], v[54:55] op_sel_hi:[1,0]
	v_pk_mul_f32 v[36:37], v[36:37], v[44:45]
	v_pk_mul_f32 v[44:45], v[46:47], v[50:51]
	v_mul_f32_e32 v46, 0xbfb8aa3b, v40
	v_mul_f32_e32 v47, 0xbfb8aa3b, v41
	v_exp_f32_e32 v46, v46
	v_exp_f32_e32 v47, v47
	v_pk_mul_f32 v[38:39], v[38:39], v[54:55] op_sel_hi:[1,0]
	v_pk_mul_f32 v[42:43], v[42:43], v[54:55] op_sel_hi:[1,0]
	v_pk_mul_f32 v[38:39], v[38:39], v[44:45]
	v_add_f32_e32 v44, 1.0, v46
	v_add_f32_e32 v45, 1.0, v47
	v_mul_f32_e32 v46, 0xbfb8aa3b, v42
	v_mul_f32_e32 v47, 0xbfb8aa3b, v43
	v_exp_f32_e32 v46, v46
	v_exp_f32_e32 v47, v47
	v_rcp_f32_e32 v44, v44
	v_rcp_f32_e32 v45, v45
	v_add_f32_e32 v46, 1.0, v46
	v_add_f32_e32 v47, 1.0, v47
	v_rcp_f32_e32 v46, v46
	v_rcp_f32_e32 v47, v47
	v_pk_mul_f32 v[40:41], v[40:41], v[44:45]
	v_pk_mul_f32 v[32:33], v[32:33], v[54:55] op_sel_hi:[1,0]
	v_pk_mul_f32 v[34:35], v[34:35], v[54:55] op_sel_hi:[1,0]
	v_pk_mul_f32 v[40:41], v[32:33], v[40:41]
	v_pk_mul_f32 v[32:33], v[42:43], v[46:47]
	v_add_u32_e32 v44, 0x90, v144
	v_pk_mul_f32 v[42:43], v[34:35], v[32:33]
	v_cvt_pk_bf16_f32 v32, v36, v37
	v_fmamk_f32 v36, v157, 0x3a800000, v156
	v_mul_f32_e32 v37, 0x4b800000, v36
	v_cmp_gt_f32_e32 vcc, s38, v36
	v_cvt_pk_bf16_f32 v33, v38, v39
	v_cvt_pk_bf16_f32 v34, v40, v41
	v_cndmask_b32_e32 v36, v36, v37, vcc
	v_rsq_f32_e32 v38, v36
	v_mad_i64_i32 v[36:37], s[10:11], v44, s39, v[146:147]
	v_cvt_pk_bf16_f32 v35, v42, v43
	v_mul_f32_e32 v39, 0x45800000, v38
	v_cndmask_b32_e32 v38, v38, v39, vcc
	v_pk_mul_f32 v[28:29], v[28:29], v[38:39] op_sel_hi:[1,0]
	v_lshl_add_u64 v[36:37], v[36:37], 0, v[148:149]
	v_mul_f32_e32 v39, 0xbfb8aa3b, v28
	v_exp_f32_e32 v39, v39
	v_mul_f32_e32 v40, 0xbfb8aa3b, v29
	v_exp_f32_e32 v40, v40
	ds_bpermute_b32 v206, v216, v36
	ds_bpermute_b32 v207, v216, v37
	ds_bpermute_b32 v212, v216, v32
	ds_bpermute_b32 v213, v216, v33
	ds_bpermute_b32 v214, v216, v34
	ds_bpermute_b32 v215, v216, v35
	s_waitcnt lgkmcnt(6)
; DI float sigmoidf_(float v) { return __builtin_amdgcn_rcpf(1.f + __builtin_amdgcn_exp2f(-v * 1.4426950408889634f)); }
; DI u32x4 pack8(f32x4 a, f32x4 b) { u32x4 w; w.x = cvtpk(a[0], a[1]); w.y = cvtpk(a[2], a[3]); w.z = cvtpk(b[0], b[1]); w.w = cvtpk(b[2], b[3]); return w; }
;   DI void operator()(const f32x4 (&acc)[2][2][4][2], const Unit& u, int wr, int wc, int fr, int fq) const {
;     const int row0 = u.pm * 256 + wr * 64 + fr; const int hcol = u.pn * 128 + wc * 32 + 8 * fq;
;     float rs[8];
; #pragma unroll
;     for (int i = 0; i < 8; ++i) rs[i] = ssq[row0 + (i >> 2) * 128 + (i & 3) * 16];
; #pragma unroll
;     for (int ai = 0; ai < 2; ++ai)
; #pragma unroll
;       for (int m = 0; m < 4; ++m) {
;         const int row = row0 + ai * 128 + m * 16;
;         const float rstd = rsqrtf(rs[ai * 4 + m] * (1.f / DM) + EPSN);
;         f32x4 o[2];
; #pragma unroll
;         for (int n = 0; n < 2; ++n) {
;           const f32x4 a = acc[ai][0][m][n] * rstd, b = acc[ai][1][m][n] * rstd;
; #pragma unroll
;           for (int e = 0; e < 4; ++e) o[n][e] = a[e] * sigmoidf_(a[e]) * b[e];
;         }
;         __builtin_nontemporal_store(pack8(o[0], o[1]), (u32x4*)(H + (size_t)row * DFF + hcol));
;       }
	global_store_dwordx4 v[204:205], v[208:211], off nt
	v_pk_mul_f32 v[30:31], v[30:31], v[38:39] op_sel_hi:[1,0]
	v_pk_mul_f32 v[20:21], v[20:21], v[38:39] op_sel_hi:[1,0]
	v_mul_f32_e32 v34, 0xbfb8aa3b, v30
	v_mul_f32_e32 v35, 0xbfb8aa3b, v31
	v_exp_f32_e32 v34, v34
	v_exp_f32_e32 v35, v35
	v_add_f32_e32 v32, 1.0, v39
	v_add_f32_e32 v33, 1.0, v40
	v_rcp_f32_e32 v32, v32
	v_rcp_f32_e32 v33, v33
	v_add_f32_e32 v34, 1.0, v34
	v_add_f32_e32 v35, 1.0, v35
	v_rcp_f32_e32 v34, v34
	v_rcp_f32_e32 v35, v35
	v_pk_mul_f32 v[28:29], v[28:29], v[32:33]
	v_pk_mul_f32 v[24:25], v[24:25], v[38:39] op_sel_hi:[1,0]
	v_pk_mul_f32 v[20:21], v[20:21], v[28:29]
	v_pk_mul_f32 v[28:29], v[30:31], v[34:35]
	v_mul_f32_e32 v30, 0xbfb8aa3b, v24
	v_mul_f32_e32 v31, 0xbfb8aa3b, v25
	v_exp_f32_e32 v30, v30
	v_exp_f32_e32 v31, v31
	v_pk_mul_f32 v[22:23], v[22:23], v[38:39] op_sel_hi:[1,0]
	v_pk_mul_f32 v[26:27], v[26:27], v[38:39] op_sel_hi:[1,0]
	v_pk_mul_f32 v[22:23], v[22:23], v[28:29]
	v_add_f32_e32 v28, 1.0, v30
	v_add_f32_e32 v29, 1.0, v31
	v_mul_f32_e32 v30, 0xbfb8aa3b, v26
	v_mul_f32_e32 v31, 0xbfb8aa3b, v27
	v_exp_f32_e32 v30, v30
	v_exp_f32_e32 v31, v31
	v_rcp_f32_e32 v28, v28
	v_rcp_f32_e32 v29, v29
	v_add_f32_e32 v30, 1.0, v30
	v_add_f32_e32 v31, 1.0, v31
	v_rcp_f32_e32 v30, v30
	v_rcp_f32_e32 v31, v31
	v_pk_mul_f32 v[24:25], v[24:25], v[28:29]
	v_pk_mul_f32 v[16:17], v[16:17], v[38:39] op_sel_hi:[1,0]
	v_pk_mul_f32 v[18:19], v[18:19], v[38:39] op_sel_hi:[1,0]
	v_pk_mul_f32 v[24:25], v[16:17], v[24:25]
	v_pk_mul_f32 v[16:17], v[26:27], v[30:31]
	v_add_u32_e32 v28, 0xa0, v144
	v_pk_mul_f32 v[26:27], v[18:19], v[16:17]
	v_cvt_pk_bf16_f32 v16, v20, v21
	v_fmamk_f32 v20, v145, 0x3a800000, v156
	v_mul_f32_e32 v21, 0x4b800000, v20
	v_cmp_gt_f32_e32 vcc, s38, v20
	v_cvt_pk_bf16_f32 v17, v22, v23
	v_cvt_pk_bf16_f32 v18, v24, v25
	v_cndmask_b32_e32 v20, v20, v21, vcc
	v_rsq_f32_e32 v22, v20
	v_mad_i64_i32 v[20:21], s[10:11], v28, s39, v[146:147]
	v_cvt_pk_bf16_f32 v19, v26, v27
	v_mul_f32_e32 v23, 0x45800000, v22
	v_cndmask_b32_e32 v22, v22, v23, vcc
	v_pk_mul_f32 v[12:13], v[12:13], v[22:23] op_sel_hi:[1,0]
	v_lshl_add_u64 v[20:21], v[20:21], 0, v[148:149]
	v_mul_f32_e32 v23, 0xbfb8aa3b, v12
	v_exp_f32_e32 v23, v23
	v_mul_f32_e32 v24, 0xbfb8aa3b, v13
	v_exp_f32_e32 v24, v24
	ds_bpermute_b32 v204, v216, v20
	ds_bpermute_b32 v205, v216, v21
	ds_bpermute_b32 v208, v216, v16
	ds_bpermute_b32 v209, v216, v17
	ds_bpermute_b32 v210, v216, v18
	ds_bpermute_b32 v211, v216, v19
	s_waitcnt lgkmcnt(6)
	global_store_dwordx4 v[206:207], v[212:215], off nt
	v_pk_mul_f32 v[14:15], v[14:15], v[22:23] op_sel_hi:[1,0]
	v_pk_mul_f32 v[4:5], v[4:5], v[22:23] op_sel_hi:[1,0]
	v_mul_f32_e32 v18, 0xbfb8aa3b, v14
	v_mul_f32_e32 v19, 0xbfb8aa3b, v15
	v_exp_f32_e32 v18, v18
	v_exp_f32_e32 v19, v19
	v_add_f32_e32 v16, 1.0, v23
	v_add_f32_e32 v17, 1.0, v24
	v_rcp_f32_e32 v16, v16
	v_rcp_f32_e32 v17, v17
	v_add_f32_e32 v18, 1.0, v18
	v_add_f32_e32 v19, 1.0, v19
	v_rcp_f32_e32 v18, v18
	v_rcp_f32_e32 v19, v19
	v_pk_mul_f32 v[12:13], v[12:13], v[16:17]
	v_pk_mul_f32 v[8:9], v[8:9], v[22:23] op_sel_hi:[1,0]
	v_pk_mul_f32 v[4:5], v[4:5], v[12:13]
	v_pk_mul_f32 v[12:13], v[14:15], v[18:19]
	v_mul_f32_e32 v14, 0xbfb8aa3b, v8
	v_mul_f32_e32 v15, 0xbfb8aa3b, v9
	v_exp_f32_e32 v14, v14
	v_exp_f32_e32 v15, v15
	v_pk_mul_f32 v[6:7], v[6:7], v[22:23] op_sel_hi:[1,0]
	v_pk_mul_f32 v[10:11], v[10:11], v[22:23] op_sel_hi:[1,0]
	v_pk_mul_f32 v[6:7], v[6:7], v[12:13]
	v_add_f32_e32 v12, 1.0, v14
	v_add_f32_e32 v13, 1.0, v15
	v_mul_f32_e32 v14, 0xbfb8aa3b, v10
	v_mul_f32_e32 v15, 0xbfb8aa3b, v11
	v_exp_f32_e32 v14, v14
	v_exp_f32_e32 v15, v15
	v_rcp_f32_e32 v12, v12
	v_rcp_f32_e32 v13, v13
	v_add_f32_e32 v14, 1.0, v14
	v_add_f32_e32 v15, 1.0, v15
	v_rcp_f32_e32 v14, v14
	v_rcp_f32_e32 v15, v15
	v_pk_mul_f32 v[8:9], v[8:9], v[12:13]
	v_pk_mul_f32 v[0:1], v[0:1], v[22:23] op_sel_hi:[1,0]
	v_pk_mul_f32 v[2:3], v[2:3], v[22:23] op_sel_hi:[1,0]
	v_pk_mul_f32 v[8:9], v[0:1], v[8:9]
	v_pk_mul_f32 v[0:1], v[10:11], v[14:15]
	v_add_u32_e32 v12, 0xb0, v144
	v_pk_mul_f32 v[10:11], v[2:3], v[0:1]
	v_cvt_pk_bf16_f32 v0, v4, v5
	v_mad_i64_i32 v[4:5], s[10:11], v12, s39, v[146:147]
	v_cvt_pk_bf16_f32 v1, v6, v7
	v_cvt_pk_bf16_f32 v2, v8, v9
	v_cvt_pk_bf16_f32 v3, v10, v11
	v_lshl_add_u64 v[4:5], v[4:5], 0, v[148:149]
	s_andn2_b64 vcc, exec, s[8:9]
	s_mov_b64 s[8:9], -1
	ds_bpermute_b32 v206, v216, v4
	ds_bpermute_b32 v207, v216, v5
	ds_bpermute_b32 v212, v216, v0
	ds_bpermute_b32 v213, v216, v1
	ds_bpermute_b32 v214, v216, v2
	ds_bpermute_b32 v215, v216, v3
	s_waitcnt lgkmcnt(6)
	global_store_dwordx4 v[204:205], v[208:211], off nt
	s_waitcnt lgkmcnt(0)
	global_store_dwordx4 v[206:207], v[212:215], off nt
	s_cbranch_vccnz .LBB0_1249
	s_andn2_b64 vcc, exec, s[0:1]
	s_cbranch_vccnz .LBB0_1248
	s_barrier
	s_branch .LBB0_1248
